# final RMSNorm loop: next iteration's loads prefetched into a second register set before the current iteration's compute and stores
# baseline (speedup 1.0000x reference)
; DI float bflo(unsigned v) { return __uint_as_float(v << 16); }
; DI float bfhi(unsigned v) { return __uint_as_float(v & 0xffff0000u); }
; __global__ void __launch_bounds__(256, 2) hymba_mega(Params p) {
;     ...
;     for (int row0 = (bid * 4 + (tid >> 6)) * 4; row0 < MTOK; row0 += nb * 16) {
;       f32x4 xv[4][4];
;       float rs[4];
; #pragma unroll
;       for (int q = 0; q < 4; ++q) {
;         rs[q] = ssf[row0 + q];
; #pragma unroll
;         for (int j = 0; j < 4; ++j) {
;           const u32x2 xb = __builtin_nontemporal_load((const u32x2*)((const u16*)p.x2 + (size_t)(row0 + q) * DM + j * 256 + lane * 4));
;           xv[q][j][0] = bflo(xb[0]); xv[q][j][1] = bfhi(xb[0]); xv[q][j][2] = bflo(xb[1]); xv[q][j][3] = bfhi(xb[1]);
;         }
;       }
; #pragma unroll
;       for (int q = 0; q < 4; ++q) {
;         const float rq = __builtin_amdgcn_rsqf(rs[q] * (1.f / DM) + EPS);
; #pragma unroll
;         for (int j = 0; j < 4; ++j) {
;           f32x4 v = xv[q][j];
;           v[0] *= rq * gv[j][0]; v[1] *= rq * gv[j][1]; v[2] *= rq * gv[j][2]; v[3] *= rq * gv[j][3];
;           __builtin_nontemporal_store(v, (f32x4*)(p.out + (size_t)(row0 + q) * DM + j * 256 + lane * 4));
.Lfin_loop:
	v_add_co_u32_e32 v38, vcc, s8, v24
	v_add_u32_e32 v20, s12, v20
	s_nop 0
	v_addc_co_u32_e32 v39, vcc, 0, v25, vcc
	v_add_co_u32_e32 v40, vcc, s9, v24
	v_lshl_add_u64 v[22:23], v[22:23], 0, s[0:1]
	s_nop 0
	v_addc_co_u32_e32 v41, vcc, 0, v25, vcc
	v_add_co_u32_e32 v94, vcc, s10, v24
	v_lshl_add_u64 v[26:27], v[26:27], 0, s[4:5]
	s_nop 0
	v_addc_co_u32_e32 v95, vcc, 0, v25, vcc
	v_cmp_lt_i32_e32 vcc, s11, v20
	s_or_b64 s[6:7], vcc, s[6:7]
	s_mov_b64 s[14:15], exec
	s_andn2_b64 exec, exec, s[6:7]
	global_load_dwordx4 v[236:239], v[22:23], off
	global_load_dwordx2 v[200:201], v[26:27], off offset:-4096 nt
	global_load_dwordx2 v[202:203], v[26:27], off offset:-3584 nt
	global_load_dwordx2 v[204:205], v[26:27], off offset:-3072 nt
	global_load_dwordx2 v[206:207], v[26:27], off offset:-2560 nt
	global_load_dwordx2 v[208:209], v[26:27], off offset:-2048 nt
	global_load_dwordx2 v[210:211], v[26:27], off offset:-1536 nt
	global_load_dwordx2 v[212:213], v[26:27], off offset:-1024 nt
	global_load_dwordx2 v[214:215], v[26:27], off offset:-512 nt
	global_load_dwordx2 v[216:217], v[26:27], off nt
	global_load_dwordx2 v[218:219], v[26:27], off offset:512 nt
	global_load_dwordx2 v[220:221], v[26:27], off offset:1024 nt
	global_load_dwordx2 v[222:223], v[26:27], off offset:1536 nt
	global_load_dwordx2 v[224:225], v[26:27], off offset:2048 nt
	global_load_dwordx2 v[226:227], v[26:27], off offset:2560 nt
	global_load_dwordx2 v[228:229], v[26:27], off offset:3072 nt
	global_load_dwordx2 v[230:231], v[26:27], off offset:3584 nt
	s_mov_b64 exec, s[14:15]
	s_waitcnt vmcnt(33)
	v_fmamk_f32 v16, v16, 0x3a800000, v21
	v_fmamk_f32 v17, v17, 0x3a800000, v21
	v_fmamk_f32 v19, v19, 0x3a800000, v21
	v_rsq_f32_e32 v16, v16
	s_waitcnt vmcnt(32)
	v_lshlrev_b32_e32 v64, 16, v62
	v_and_b32_e32 v65, 0xffff0000, v62
	v_lshlrev_b32_e32 v62, 16, v63
	v_and_b32_e32 v63, 0xffff0000, v63
	s_waitcnt vmcnt(25)
	v_lshlrev_b32_e32 v80, 16, v48
	v_and_b32_e32 v81, 0xffff0000, v48
	v_fmamk_f32 v48, v18, 0x3a800000, v21
	v_rsq_f32_e32 v18, v17
	v_lshlrev_b32_e32 v66, 16, v60
	s_waitcnt vmcnt(20)
	v_lshlrev_b32_e32 v100, 16, v34
	v_and_b32_e32 v101, 0xffff0000, v34
	s_waitcnt vmcnt(18)
	v_lshlrev_b32_e32 v108, 16, v30
	v_and_b32_e32 v109, 0xffff0000, v30
	s_waitcnt vmcnt(17)
	v_lshlrev_b32_e32 v112, 16, v28
	v_and_b32_e32 v113, 0xffff0000, v28
	v_rsq_f32_e32 v28, v48
	v_rsq_f32_e32 v30, v19
	v_lshlrev_b32_e32 v102, 16, v35
	v_and_b32_e32 v103, 0xffff0000, v35
	v_lshlrev_b32_e32 v104, 16, v32
	v_and_b32_e32 v105, 0xffff0000, v32
	v_lshlrev_b32_e32 v106, 16, v33
	v_and_b32_e32 v107, 0xffff0000, v33
	v_mul_f32_e32 v32, v16, v12
	v_mul_f32_e32 v33, v16, v13
	v_mul_f32_e32 v34, v16, v14
	v_mul_f32_e32 v35, v16, v15
	v_and_b32_e32 v67, 0xffff0000, v60
	v_lshlrev_b32_e32 v60, 16, v61
	v_and_b32_e32 v61, 0xffff0000, v61
	v_lshlrev_b32_e32 v68, 16, v58
	v_and_b32_e32 v69, 0xffff0000, v58
	v_lshlrev_b32_e32 v58, 16, v59
	v_and_b32_e32 v59, 0xffff0000, v59
	v_lshlrev_b32_e32 v70, 16, v56
	v_and_b32_e32 v71, 0xffff0000, v56
	v_lshlrev_b32_e32 v56, 16, v57
	v_and_b32_e32 v57, 0xffff0000, v57
	v_lshlrev_b32_e32 v72, 16, v54
	v_and_b32_e32 v73, 0xffff0000, v54
	v_lshlrev_b32_e32 v54, 16, v55
	v_and_b32_e32 v55, 0xffff0000, v55
	v_lshlrev_b32_e32 v74, 16, v52
	v_and_b32_e32 v75, 0xffff0000, v52
	v_lshlrev_b32_e32 v52, 16, v53
	v_and_b32_e32 v53, 0xffff0000, v53
	v_lshlrev_b32_e32 v76, 16, v50
	v_and_b32_e32 v77, 0xffff0000, v50
	v_lshlrev_b32_e32 v78, 16, v51
	v_and_b32_e32 v79, 0xffff0000, v51
	v_lshlrev_b32_e32 v82, 16, v49
	v_and_b32_e32 v83, 0xffff0000, v49
	v_lshlrev_b32_e32 v84, 16, v46
	v_and_b32_e32 v85, 0xffff0000, v46
	v_lshlrev_b32_e32 v86, 16, v47
	v_and_b32_e32 v87, 0xffff0000, v47
	v_lshlrev_b32_e32 v88, 16, v44
	v_and_b32_e32 v89, 0xffff0000, v44
	v_lshlrev_b32_e32 v90, 16, v45
	v_and_b32_e32 v91, 0xffff0000, v45
	v_lshlrev_b32_e32 v92, 16, v42
	v_and_b32_e32 v93, 0xffff0000, v42
	v_lshlrev_b32_e32 v96, 16, v43
	v_and_b32_e32 v97, 0xffff0000, v43
	v_lshlrev_b32_e32 v98, 16, v36
	v_and_b32_e32 v99, 0xffff0000, v36
	v_lshlrev_b32_e32 v36, 16, v37
	v_and_b32_e32 v37, 0xffff0000, v37
	v_lshlrev_b32_e32 v110, 16, v31
	v_and_b32_e32 v111, 0xffff0000, v31
	v_lshlrev_b32_e32 v114, 16, v29
	v_and_b32_e32 v115, 0xffff0000, v29
	v_mul_f32_e32 v42, v16, v8
	v_mul_f32_e32 v43, v16, v9
	v_mul_f32_e32 v44, v16, v10
	v_mul_f32_e32 v45, v16, v11
	v_mul_f32_e32 v46, v16, v4
	v_mul_f32_e32 v47, v16, v5
	v_mul_f32_e32 v48, v16, v6
	v_mul_f32_e32 v49, v16, v7
	v_mul_f32_e32 v50, v16, v0
	v_mul_f32_e32 v51, v16, v1
	v_mul_f32_e32 v116, v16, v2
	v_mul_f32_e32 v117, v16, v3
	v_mul_f32_e32 v118, v18, v12
	v_mul_f32_e32 v119, v18, v13
	v_mul_f32_e32 v120, v18, v14
	v_mul_f32_e32 v121, v18, v15
	v_mul_f32_e32 v122, v18, v8
	v_mul_f32_e32 v123, v18, v9
	v_mul_f32_e32 v124, v18, v10
	v_mul_f32_e32 v125, v18, v11
	v_mul_f32_e32 v126, v18, v4
	v_mul_f32_e32 v127, v18, v5
	v_mul_f32_e32 v128, v18, v6
	v_mul_f32_e32 v129, v18, v7
; __global__ void __launch_bounds__(256, 2) hymba_mega(Params p) {
;     ...
; #pragma unroll
;       for (int q = 0; q < 4; ++q) {
;         const float rq = __builtin_amdgcn_rsqf(rs[q] * (1.f / DM) + EPS);
; #pragma unroll
;         for (int j = 0; j < 4; ++j) {
;           f32x4 v = xv[q][j];
;           v[0] *= rq * gv[j][0]; v[1] *= rq * gv[j][1]; v[2] *= rq * gv[j][2]; v[3] *= rq * gv[j][3];
;           __builtin_nontemporal_store(v, (f32x4*)(p.out + (size_t)(row0 + q) * DM + j * 256 + lane * 4));
;         }
;       }
;     }
	v_mul_f32_e32 v130, v18, v0
	v_mul_f32_e32 v131, v18, v1
	v_mul_f32_e32 v132, v18, v2
	v_mul_f32_e32 v133, v18, v3
	v_mul_f32_e32 v134, v28, v12
	v_mul_f32_e32 v135, v28, v13
	v_mul_f32_e32 v136, v28, v14
	v_mul_f32_e32 v137, v28, v15
	v_mul_f32_e32 v138, v28, v8
	v_mul_f32_e32 v139, v28, v9
	v_mul_f32_e32 v140, v28, v10
	v_mul_f32_e32 v141, v28, v11
	v_mul_f32_e32 v142, v28, v4
	v_mul_f32_e32 v143, v28, v5
	v_mul_f32_e32 v144, v28, v6
	v_mul_f32_e32 v145, v28, v7
	v_mul_f32_e32 v146, v28, v0
	v_mul_f32_e32 v147, v28, v1
	v_mul_f32_e32 v148, v28, v2
	v_mul_f32_e32 v149, v28, v3
	v_mul_f32_e32 v150, v30, v12
	v_mul_f32_e32 v151, v30, v13
	v_mul_f32_e32 v152, v30, v14
	v_mul_f32_e32 v153, v30, v15
	v_mul_f32_e32 v154, v30, v8
	v_mul_f32_e32 v155, v30, v9
	v_mul_f32_e32 v156, v30, v10
	v_mul_f32_e32 v157, v30, v11
	v_mul_f32_e32 v158, v30, v4
	v_mul_f32_e32 v159, v30, v5
	v_mul_f32_e32 v160, v30, v6
	v_mul_f32_e32 v161, v30, v7
	v_mul_f32_e32 v162, v30, v0
	v_mul_f32_e32 v163, v30, v1
	v_mul_f32_e32 v164, v30, v2
	v_mul_f32_e32 v165, v30, v3
	v_mul_f32_e32 v16, v32, v64
	v_mul_f32_e32 v17, v33, v65
	v_mul_f32_e32 v18, v34, v62
	v_mul_f32_e32 v19, v35, v63
	v_mul_f32_e32 v28, v42, v66
	v_mul_f32_e32 v29, v43, v67
	v_mul_f32_e32 v30, v44, v60
	v_mul_f32_e32 v31, v45, v61
	v_mul_f32_e32 v32, v46, v68
	v_mul_f32_e32 v33, v47, v69
	v_mul_f32_e32 v34, v48, v58
	v_mul_f32_e32 v35, v49, v59
	v_mul_f32_e32 v42, v50, v70
	v_mul_f32_e32 v43, v51, v71
	v_mul_f32_e32 v44, v116, v56
	v_mul_f32_e32 v45, v117, v57
	v_mul_f32_e32 v46, v118, v72
	v_mul_f32_e32 v47, v119, v73
	v_mul_f32_e32 v48, v120, v54
	v_mul_f32_e32 v49, v121, v55
	v_mul_f32_e32 v50, v122, v74
	v_mul_f32_e32 v51, v123, v75
	v_mul_f32_e32 v52, v124, v52
	v_mul_f32_e32 v53, v125, v53
	v_mul_f32_e32 v54, v126, v76
	v_mul_f32_e32 v55, v127, v77
	v_mul_f32_e32 v56, v128, v78
	v_mul_f32_e32 v57, v129, v79
	v_mul_f32_e32 v58, v130, v80
	v_mul_f32_e32 v59, v131, v81
	v_mul_f32_e32 v60, v132, v82
	v_mul_f32_e32 v61, v133, v83
	v_mul_f32_e32 v62, v134, v84
	v_mul_f32_e32 v63, v135, v85
	v_mul_f32_e32 v64, v136, v86
	v_mul_f32_e32 v65, v137, v87
	v_mul_f32_e32 v66, v138, v88
	v_mul_f32_e32 v67, v139, v89
	v_mul_f32_e32 v68, v140, v90
	v_mul_f32_e32 v69, v141, v91
	v_mul_f32_e32 v70, v142, v92
	v_mul_f32_e32 v71, v143, v93
	v_mul_f32_e32 v72, v144, v96
	v_mul_f32_e32 v73, v145, v97
	v_mul_f32_e32 v74, v146, v98
	v_mul_f32_e32 v75, v147, v99
	v_mul_f32_e32 v76, v148, v36
	v_mul_f32_e32 v77, v149, v37
	v_mul_f32_e32 v78, v150, v100
	v_mul_f32_e32 v79, v151, v101
	v_mul_f32_e32 v80, v152, v102
	v_mul_f32_e32 v81, v153, v103
	v_mul_f32_e32 v82, v154, v104
	v_mul_f32_e32 v83, v155, v105
	v_mul_f32_e32 v84, v156, v106
	v_mul_f32_e32 v85, v157, v107
	v_mul_f32_e32 v86, v158, v108
	v_mul_f32_e32 v87, v159, v109
	v_mul_f32_e32 v88, v160, v110
	v_mul_f32_e32 v89, v161, v111
	v_mul_f32_e32 v90, v162, v112
	v_mul_f32_e32 v91, v163, v113
	v_mul_f32_e32 v92, v164, v114
	v_mul_f32_e32 v93, v165, v115
	global_store_dwordx4 v[24:25], v[16:19], off nt
	global_store_dwordx4 v[24:25], v[28:31], off offset:1024 nt
	global_store_dwordx4 v[24:25], v[32:35], off offset:2048 nt
	global_store_dwordx4 v[24:25], v[42:45], off offset:3072 nt
	global_store_dwordx4 v[40:41], v[46:49], off offset:-4096 nt
	global_store_dwordx4 v[38:39], v[50:53], off offset:1024 nt
	global_store_dwordx4 v[38:39], v[54:57], off offset:2048 nt
	global_store_dwordx4 v[38:39], v[58:61], off offset:3072 nt
	global_store_dwordx4 v[40:41], v[62:65], off nt
	global_store_dwordx4 v[40:41], v[66:69], off offset:1024 nt
	global_store_dwordx4 v[40:41], v[70:73], off offset:2048 nt
	global_store_dwordx4 v[40:41], v[74:77], off offset:3072 nt
	global_store_dwordx4 v[94:95], v[78:81], off nt
	global_store_dwordx4 v[94:95], v[82:85], off offset:1024 nt
	global_store_dwordx4 v[94:95], v[86:89], off offset:2048 nt
	global_store_dwordx4 v[94:95], v[90:93], off offset:3072 nt
	v_lshl_add_u64 v[24:25], v[24:25], 0, s[2:3]
	s_andn2_b64 exec, exec, s[6:7]
	s_cbranch_execz .LBB0_525
	s_waitcnt vmcnt(16)
	v_mov_b32_e32 v16, v236
	v_mov_b32_e32 v17, v237
	v_mov_b32_e32 v18, v238
	v_mov_b32_e32 v19, v239
	v_mov_b32_e32 v28, v230
	v_mov_b32_e32 v29, v231
	v_mov_b32_e32 v30, v228
	v_mov_b32_e32 v31, v229
	v_mov_b32_e32 v32, v226
	v_mov_b32_e32 v33, v227
	v_mov_b32_e32 v34, v224
	v_mov_b32_e32 v35, v225
	v_mov_b32_e32 v36, v222
	v_mov_b32_e32 v37, v223
	v_mov_b32_e32 v42, v220
	v_mov_b32_e32 v43, v221
	v_mov_b32_e32 v44, v218
	v_mov_b32_e32 v45, v219
	v_mov_b32_e32 v46, v216
	v_mov_b32_e32 v47, v217
	v_mov_b32_e32 v48, v214
	v_mov_b32_e32 v49, v215
	v_mov_b32_e32 v50, v212
	v_mov_b32_e32 v51, v213
	v_mov_b32_e32 v52, v210
	v_mov_b32_e32 v53, v211
	v_mov_b32_e32 v54, v208
	v_mov_b32_e32 v55, v209
	v_mov_b32_e32 v56, v206
	v_mov_b32_e32 v57, v207
	v_mov_b32_e32 v58, v204
	v_mov_b32_e32 v59, v205
	v_mov_b32_e32 v60, v202
	v_mov_b32_e32 v61, v203
	v_mov_b32_e32 v62, v200
	v_mov_b32_e32 v63, v201
	s_branch .Lfin_loop
